# P0->P1 seam: one-shot two-level barrier, start-of-kernel zeroing written through and a read-as-zero guard before any count
# baseline (speedup 1.0000x reference)
; __global__ void __launch_bounds__(NWAVES * 64, 2) fwd_mega(Args args) {
;     ...
;     if (lo == 0) { unsigned* bz = (unsigned*)(ws + WS_BAR); for (int i = blockIdx.x * (NWAVES * 64) + threadIdx.x; i < BAR_BYTES / 4; i += gridDim.x * (NWAVES * 64)) bz[i] = 0u; }
.LBB0_6:
	v_ashrrev_i32_e32 v3, 31, v2
	v_lshl_add_u64 v[4:5], v[2:3], 2, s[4:5]
	v_add_u32_e32 v2, s8, v2
	v_cmp_lt_i32_e32 vcc, s9, v2
	s_or_b64 s[6:7], vcc, s[6:7]
	global_store_dword v[4:5], v1, off sc0 sc1
	s_andn2_b64 exec, exec, s[6:7]
	s_cbranch_execnz .LBB0_6

; #define LAS __attribute__((address_space(3)))
; #define PH_IDS() int tid = threadIdx.x; asm volatile("" : "+v"(tid)); const int lane = tid & 63
; #define SEAM(k) do { if (IN(k) && IN((k) + 1)) { if ((k) == 0) cg::this_grid().sync(); else xcd_barrier(xbar); } } while (0)
; __global__ void __launch_bounds__(NWAVES * 64, 2) fwd_mega(Args args) {
;     ...
;     { volatile LAS unsigned* m_ = (volatile LAS unsigned*)(lds + MISC_OFF); if (threadIdx.x < 16) m_[threadIdx.x] = 0u; }
;     __syncthreads();
;     if (lo == 0) { unsigned* bz = (unsigned*)(ws + WS_BAR); for (int i = blockIdx.x * (NWAVES * 64) + threadIdx.x; i < BAR_BYTES / 4; i += gridDim.x * (NWAVES * 64)) bz[i] = 0u; }
;     XcdBarrier xbar; xbar.bar = (unsigned*)(ws + WS_BAR); xbar.x = 0; xbar.st = (volatile LAS unsigned*)(lds + MISC_OFF);
;     bf16* XN = (bf16*)args.out;
;     bf16* AO = (bf16*)(ws + WS_AO); bf16* VA = (bf16*)(ws + WS_VA); bf16* ZA = (bf16*)(ws + WS_ZA); bf16* KB = (bf16*)(ws + WS_K); bf16* VB = (bf16*)(ws + WS_V); bf16* ZB = (bf16*)(ws + WS_ZB);
;     bf16* GA = VA; bf16* GB = ZA; bf16* MG = KB;
;     float* ssq = (float*)(ws + WS_SSQ); float* logf_ = (float*)(ws + WS_LOGF); float* cc = (float*)(ws + WS_CC);
;     if (IN(0)) { PH_IDS(); p0_prologue(args, lds, vcu, G, tid, lane, wave); __syncthreads(); }
;     SEAM(0);
.LBB0_62:
	s_cmp_gt_i32 s31, 1
	s_cselect_b64 s[4:5], -1, 0
	s_and_b64 s[0:1], s[22:23], s[4:5]
	s_andn2_b64 vcc, exec, s[0:1]
	v_cmp_eq_u32_e64 s[0:1], 0, v0
	s_cbranch_vccnz .LBB0_74
	s_barrier
	s_and_saveexec_b64 s[6:7], s[0:1]
	s_cbranch_execz .LBB0_73
	s_add_u32 s8, s28, 0x84000
	s_addc_u32 s9, s29, 0
	s_and_b32 s10, s2, 7
	s_lshl_b32 s10, s10, 8
	s_add_u32 s10, s8, s10
	s_addc_u32 s11, s9, 0
	v_mov_b32_e32 v1, 0
	v_mov_b32_e32 v2, 1
	global_load_dword v4, v1, s[10:11] offset:64 sc1
	global_load_dword v5, v1, s[8:9] offset:2112 sc1
	buffer_wbl2 sc1
	s_waitcnt vmcnt(0)
	v_readfirstlane_b32 s12, v4
	s_cmp_eq_u32 s12, 0
	s_cbranch_scc1 .Lgs_z1_ok
	s_mov_b32 s13, 0
.Lgs_z1:
	s_sleep 1
	global_load_dword v3, v1, s[10:11] offset:64 sc1
	s_waitcnt vmcnt(0)
	v_readfirstlane_b32 s12, v3
	s_add_u32 s13, s13, 1
	s_cmp_eq_u32 s12, 0
	s_cbranch_scc1 .Lgs_z1_ok
	s_cmp_lt_u32 s13, 0x4000
	s_cbranch_scc1 .Lgs_z1
.Lgs_z1_ok:
	global_atomic_add v3, v1, v2, s[10:11] offset:32 sc0
	s_waitcnt vmcnt(0)
	v_readfirstlane_b32 s12, v3
	s_cmp_lg_u32 s12, 31
	s_cbranch_scc1 .Lgs_member
	v_readfirstlane_b32 s12, v5
	s_cmp_eq_u32 s12, 0
	s_cbranch_scc1 .Lgs_z2_ok
	s_mov_b32 s13, 0
.Lgs_z2:
	s_sleep 1
	global_load_dword v3, v1, s[8:9] offset:2112 sc1
	s_waitcnt vmcnt(0)
	v_readfirstlane_b32 s12, v3
	s_add_u32 s13, s13, 1
	s_cmp_eq_u32 s12, 0
	s_cbranch_scc1 .Lgs_z2_ok
	s_cmp_lt_u32 s13, 0x4000
	s_cbranch_scc1 .Lgs_z2
.Lgs_z2_ok:
	global_atomic_add v3, v1, v2, s[8:9] offset:2080 sc0
	s_waitcnt vmcnt(0)
	v_readfirstlane_b32 s12, v3
	s_cmp_lg_u32 s12, 7
	s_cbranch_scc1 .Lgs_leader_wait
	global_atomic_add v1, v2, s[8:9] offset:2112
	s_branch .Lgs_leader_go
